# readout0 epilogue: block (0,0) addresses as before, other 15 blocks by +row-block*0x10000 +col-block*64; gate quads deduplicated, residual rows loaded in two batches of 8 blocks
# speedup vs baseline: 1.0077x; 1.0077x over previous
.LBB0_536:
	v_add_u32_e32 v76, s10, v156
	v_mul_hi_i32 v65, v76, s97
	v_lshrrev_b32_e32 v66, 31, v65
	v_ashrrev_i32_e32 v65, 11, v65
	v_add_u32_e32 v65, v65, v66
	v_mul_i32_i24_e32 v66, 0x1100, v65
	v_sub_u32_e32 v69, v76, v66
	v_cmp_gt_i32_e32 vcc, s27, v69
	v_add_u32_e32 v68, s84, v65
	v_add_u32_e32 v64, s7, v157
	v_cndmask_b32_e64 v65, v68, 8, vcc
	v_mul_hi_i32_i24_e32 v67, 0x3000, v65
	v_mul_i32_i24_e32 v66, 0x3000, v65
	v_lshl_add_u64 v[66:67], s[28:29], 0, v[66:67]
	s_mov_b64 s[0:1], 0x2000
	v_ashrrev_i32_e32 v65, 31, v64
	v_lshl_add_u64 v[86:87], v[66:67], 0, s[0:1]
	v_lshlrev_b64 v[66:67], 2, v[64:65]
	v_add_u32_e32 v72, 0xffffff00, v69
	v_ashrrev_i32_e32 v73, 31, v69
	v_lshl_add_u64 v[70:71], v[86:87], 0, v[66:67]
	v_mov_b64_e32 v[112:113], v[70:71]
	v_cndmask_b32_e32 v71, 0, v73, vcc
	v_cndmask_b32_e32 v70, v72, v69, vcc
	v_ashrrev_i32_e32 v69, 31, v68
	v_cndmask_b32_e64 v72, 22, 18, vcc
	v_lshlrev_b64 v[68:69], v72, v[68:69]
	v_lshlrev_b64 v[70:71], 10, v[70:71]
	v_readlane_b32 s40, v253, 18
	v_lshl_add_u64 v[88:89], v[70:71], 0, v[68:69]
	v_readlane_b32 s41, v253, 19
	v_readlane_b32 s44, v253, 22
	v_readlane_b32 s45, v253, 23
	v_lshl_add_u64 v[68:69], v[88:89], 0, v[64:65]
	v_mov_b32_e32 v72, s41
	v_mov_b32_e32 v73, s45
	v_mov_b32_e32 v74, s40
	v_mov_b32_e32 v75, s44
	v_cndmask_b32_e32 v91, v72, v73, vcc
	v_cndmask_b32_e32 v90, v74, v75, vcc
	v_lshlrev_b64 v[92:93], 2, v[68:69]
	v_lshl_add_u64 v[68:69], v[90:91], 0, v[92:93]
	v_mov_b64_e32 v[114:115], v[68:69]
	v_mov_b32_e32 v68, s75
	v_mov_b32_e32 v69, s93
	v_mov_b32_e32 v70, s74
	v_mov_b32_e32 v71, s92
	v_cndmask_b32_e32 v95, v68, v69, vcc
	v_cndmask_b32_e32 v94, v70, v71, vcc
	s_mov_b32 s11, s6
	s_mov_b32 s7, s21
	s_mov_b32 s10, s20
	v_readlane_b32 s42, v253, 20
	v_readlane_b32 s43, v253, 21
	v_readlane_b32 s46, v253, 24
	v_readlane_b32 s47, v253, 25
	v_readlane_b32 s48, v253, 26
	v_readlane_b32 s49, v253, 27
	v_readlane_b32 s50, v253, 28
	v_readlane_b32 s51, v253, 29
	v_readlane_b32 s52, v253, 30
	v_readlane_b32 s53, v253, 31
	v_readlane_b32 s54, v253, 32
	v_readlane_b32 s55, v253, 33
	v_lshl_add_u64 v[116:117], v[94:95], 0, v[92:93]
	global_load_dwordx4 v[96:99], v[112:113], off
	global_load_dwordx4 v[100:103], v[112:113], off offset:64
	global_load_dwordx4 v[104:107], v[112:113], off offset:128
	global_load_dwordx4 v[108:111], v[112:113], off offset:192
	v_add_co_u32_e32 v118, vcc, 0x10000, v114
	s_nop 0
	v_addc_co_u32_e32 v119, vcc, 0, v115, vcc
	global_load_dwordx4 v[64:67], v[114:115], off
	global_load_dwordx4 v[68:71], v[114:115], off offset:64
	global_load_dwordx4 v[72:75], v[114:115], off offset:128
	global_load_dwordx4 v[76:79], v[114:115], off offset:192
	global_load_dwordx4 v[80:83], v[118:119], off
	global_load_dwordx4 v[84:87], v[118:119], off offset:64
	global_load_dwordx4 v[88:91], v[118:119], off offset:128
	global_load_dwordx4 v[92:95], v[118:119], off offset:192
	v_add_co_u32_e32 v120, vcc, 0x20000, v114
	s_nop 0
	v_addc_co_u32_e32 v121, vcc, 0, v115, vcc
	v_add_co_u32_e32 v122, vcc, 0x30000, v114
	s_nop 0
	v_addc_co_u32_e32 v123, vcc, 0, v115, vcc
	v_add_co_u32_e32 v124, vcc, 0x10000, v116
	s_nop 0
	v_addc_co_u32_e32 v125, vcc, 0, v117, vcc
	s_waitcnt vmcnt(0)
	v_pk_fma_f32 v[62:63], v[62:63], v[98:99], v[66:67]
	v_pk_fma_f32 v[60:61], v[60:61], v[96:97], v[64:65]
	v_pk_fma_f32 v[58:59], v[58:59], v[102:103], v[70:71]
	v_pk_fma_f32 v[56:57], v[56:57], v[100:101], v[68:69]
	v_pk_fma_f32 v[54:55], v[54:55], v[106:107], v[74:75]
	v_pk_fma_f32 v[52:53], v[52:53], v[104:105], v[72:73]
	v_pk_fma_f32 v[50:51], v[50:51], v[110:111], v[78:79]
	v_pk_fma_f32 v[48:49], v[48:49], v[108:109], v[76:77]
	v_pk_fma_f32 v[46:47], v[46:47], v[98:99], v[82:83]
	v_pk_fma_f32 v[44:45], v[44:45], v[96:97], v[80:81]
	v_pk_fma_f32 v[42:43], v[42:43], v[102:103], v[86:87]
	v_pk_fma_f32 v[40:41], v[40:41], v[100:101], v[84:85]
	v_pk_fma_f32 v[38:39], v[38:39], v[106:107], v[90:91]
	v_pk_fma_f32 v[36:37], v[36:37], v[104:105], v[88:89]
	v_pk_fma_f32 v[34:35], v[34:35], v[110:111], v[94:95]
	v_pk_fma_f32 v[32:33], v[32:33], v[108:109], v[92:93]
	global_load_dwordx4 v[64:67], v[120:121], off
	global_load_dwordx4 v[68:71], v[120:121], off offset:64
	global_load_dwordx4 v[72:75], v[120:121], off offset:128
	global_load_dwordx4 v[76:79], v[120:121], off offset:192
	global_load_dwordx4 v[80:83], v[122:123], off
	global_load_dwordx4 v[84:87], v[122:123], off offset:64
	global_load_dwordx4 v[88:91], v[122:123], off offset:128
	global_load_dwordx4 v[92:95], v[122:123], off offset:192
	global_store_dwordx4 v[116:117], v[60:63], off
	global_store_dwordx4 v[116:117], v[56:59], off offset:64
	global_store_dwordx4 v[116:117], v[52:55], off offset:128
	global_store_dwordx4 v[116:117], v[48:51], off offset:192
	global_store_dwordx4 v[124:125], v[44:47], off
	global_store_dwordx4 v[124:125], v[40:43], off offset:64
	global_store_dwordx4 v[124:125], v[36:39], off offset:128
	global_store_dwordx4 v[124:125], v[32:35], off offset:192
	v_add_co_u32_e32 v126, vcc, 0x20000, v116
	s_nop 0
	v_addc_co_u32_e32 v127, vcc, 0, v117, vcc
	v_add_co_u32_e32 v118, vcc, 0x30000, v116
	s_nop 0
	v_addc_co_u32_e32 v119, vcc, 0, v117, vcc
	s_waitcnt vmcnt(8)
	v_pk_fma_f32 v[30:31], v[30:31], v[98:99], v[66:67]
	v_pk_fma_f32 v[28:29], v[28:29], v[96:97], v[64:65]
	v_pk_fma_f32 v[26:27], v[26:27], v[102:103], v[70:71]
	v_pk_fma_f32 v[24:25], v[24:25], v[100:101], v[68:69]
	v_pk_fma_f32 v[22:23], v[22:23], v[106:107], v[74:75]
	v_pk_fma_f32 v[20:21], v[20:21], v[104:105], v[72:73]
	v_pk_fma_f32 v[18:19], v[18:19], v[110:111], v[78:79]
	v_pk_fma_f32 v[16:17], v[16:17], v[108:109], v[76:77]
	v_pk_fma_f32 v[14:15], v[14:15], v[98:99], v[82:83]
	v_pk_fma_f32 v[12:13], v[12:13], v[96:97], v[80:81]
	v_pk_fma_f32 v[10:11], v[10:11], v[102:103], v[86:87]
	v_pk_fma_f32 v[8:9], v[8:9], v[100:101], v[84:85]
	v_pk_fma_f32 v[2:3], v[2:3], v[106:107], v[90:91]
	v_pk_fma_f32 v[0:1], v[0:1], v[104:105], v[88:89]
	v_pk_fma_f32 v[6:7], v[6:7], v[110:111], v[94:95]
	v_pk_fma_f32 v[4:5], v[4:5], v[108:109], v[92:93]
	global_store_dwordx4 v[126:127], v[28:31], off
	global_store_dwordx4 v[126:127], v[24:27], off offset:64
	global_store_dwordx4 v[126:127], v[20:23], off offset:128
	global_store_dwordx4 v[126:127], v[16:19], off offset:192
	global_store_dwordx4 v[118:119], v[12:15], off
	global_store_dwordx4 v[118:119], v[8:11], off offset:64
	global_store_dwordx4 v[118:119], v[0:3], off offset:128
	global_store_dwordx4 v[118:119], v[4:7], off offset:192
	s_andn2_b64 vcc, exec, s[22:23]
	s_cbranch_vccz .LBB0_556
